# passB: the inclusive add and max scans over 64 lanes use DPP row shifts / row broadcasts instead of six dependent ds_bpermute round trips each (both units)
# speedup vs baseline: 1.0118x; 1.0073x over previous
; __device__ void passB_unit(const Params& p, LAS unsigned char* lds, int u, bool do_store = true) {
;     ...
;     if (tid < 256) { const int d = tid >> 7, i = tid & 127; sc_t = d ? 127 - i : i;
;         sc_li = GL[(size_t)(d * 8 + h) * 2048 + sc_t]; float inc = GL[(size_t)(d * 8 + 4 + h) * 2048 + sc_t];
; #pragma unroll
;         for (int off = 1; off < 64; off <<= 1) { const float n = __shfl_up(inc, off); inc += (lane >= off) ? n : 0.f; }
;         sc_b = inc; if (lane == 63) wtot[wid] = inc; }
.LBB0_533:
	s_lshl_b32 s0, s2, 1
	v_mov_b32_e32 v196, v224
	s_and_b32 s52, s0, 14
	s_movk_i32 s0, 0x100
	s_lshl_b32 s10, s52, 7
	v_ashrrev_i32_e32 v68, 6, v196
	v_and_b32_e32 v197, 63, v196
	v_cmp_gt_i32_e64 s[0:1], s0, v196
	v_mov_b32_e32 v63, 0
	v_mov_b32_e32 v69, 0
	v_mov_b32_e32 v0, 0
	s_and_saveexec_b64 s[4:5], s[0:1]
	v_readlane_b32 s40, v254, 24
	v_readlane_b32 s41, v254, 25
	s_cbranch_execz .LBB0_537
	s_ashr_i32 s41, s40, 31
	s_lshl_b64 s[6:7], s[40:41], 17
	s_add_u32 s6, s70, s6
	s_addc_u32 s7, s71, s7
	s_lshl_b32 s11, s10, 2
	s_add_u32 s6, s6, s11
	s_movk_i32 s11, 0x7f
	s_movk_i32 s24, 0x80
	v_and_b32_e32 v0, 0x7f, v196
	v_bitop3_b32 v1, v196, s11, v196 bitop3:0xc
	v_cmp_gt_u32_e32 vcc, s24, v196
	s_addc_u32 s7, s7, 0
	s_add_u32 s6, s6, 0xfc00000
	v_cndmask_b32_e32 v63, v1, v0, vcc
	v_ashrrev_i32_e32 v0, 4, v196
	v_and_or_b32 v0, v0, -8, s34
	v_or_b32_e32 v4, 4, v0
	v_ashrrev_i32_e32 v5, 31, v4
	s_addc_u32 s7, s7, 0
	v_lshlrev_b64 v[4:5], 13, v[4:5]
	v_lshlrev_b32_e32 v2, 2, v63
	v_mov_b32_e32 v3, 0
	v_lshl_add_u64 v[4:5], s[6:7], 0, v[4:5]
	v_lshl_add_u64 v[4:5], v[4:5], 0, v[2:3]
	global_load_dword v4, v[4:5], off
	v_ashrrev_i32_e32 v1, 31, v0
	v_lshlrev_b64 v[0:1], 13, v[0:1]
	v_lshl_add_u64 v[0:1], s[6:7], 0, v[0:1]
	v_lshl_add_u64 v[0:1], v[0:1], 0, v[2:3]
	global_load_dword v0, v[0:1], off
	s_waitcnt vmcnt(1)
	s_nop 1
	v_add_f32_dpp v4, v4, v4 row_shr:1 row_mask:0xf bank_mask:0xf
	s_nop 1
	v_add_f32_dpp v4, v4, v4 row_shr:2 row_mask:0xf bank_mask:0xf
	s_nop 1
	v_add_f32_dpp v4, v4, v4 row_shr:4 row_mask:0xf bank_mask:0xf
	s_nop 1
	v_add_f32_dpp v4, v4, v4 row_shr:8 row_mask:0xf bank_mask:0xf
	s_nop 1
	v_add_f32_dpp v4, v4, v4 row_bcast:15 row_mask:0xa bank_mask:0xf
	s_nop 1
	v_add_f32_dpp v4, v4, v4 row_bcast:31 row_mask:0xc bank_mask:0xf
	v_mov_b32_e32 v69, v4
	v_cmp_eq_u32_e32 vcc, 63, v197
	s_and_saveexec_b64 s[6:7], vcc
	v_lshl_add_u32 v1, v68, 2, 0
	v_add_u32_e32 v1, 0x21800, v1
	ds_write_b32 v1, v69
	s_or_b64 exec, exec, s[6:7]

; __device__ void passB_unit(const Params& p, LAS unsigned char* lds, int u, bool do_store = true) {
;     ...
;     float sc_a = 0.f, sc_pm = 0.f;
;     if (tid < 256) { if (wid & 1) sc_b += wtot[wid - 1];
;         sc_a = sc_li - sc_b; float pm = sc_a;
; #pragma unroll
;         for (int off = 1; off < 64; off <<= 1) { const float n = __shfl_up(pm, off); pm = (lane >= off) ? fmaxf(pm, n) : pm; }
;         sc_pm = pm; if (lane == 63) wmax[wid] = pm; }
.LBB0_540:
	s_or_b64 exec, exec, s[4:5]
	v_sub_f32_e32 v61, v0, v69
	v_cmp_eq_u32_e64 s[4:5], 63, v197
	v_mov_b32_e32 v70, v61
	s_nop 1
	v_max_f32_dpp v70, v70, v70 row_shr:1 row_mask:0xf bank_mask:0xf
	s_nop 1
	v_max_f32_dpp v70, v70, v70 row_shr:2 row_mask:0xf bank_mask:0xf
	s_nop 1
	v_max_f32_dpp v70, v70, v70 row_shr:4 row_mask:0xf bank_mask:0xf
	s_nop 1
	v_max_f32_dpp v70, v70, v70 row_shr:8 row_mask:0xf bank_mask:0xf
	s_nop 1
	v_max_f32_dpp v70, v70, v70 row_bcast:15 row_mask:0xa bank_mask:0xf
	s_nop 1
	v_max_f32_dpp v70, v70, v70 row_bcast:31 row_mask:0xc bank_mask:0xf
	s_and_saveexec_b64 s[10:11], s[4:5]
	v_lshl_add_u32 v2, v68, 2, 0
	v_add_u32_e32 v2, 0x21820, v2
	ds_write_b32 v2, v70
	s_or_b64 exec, exec, s[10:11]

; #define LAS __attribute__((address_space(3)))
; __device__ void passB_unit(const Params& p, LAS unsigned char* lds, int u, bool do_store = true) {
;     ...
;     if (tid < 256) { const int d = tid >> 7, i = tid & 127; sc_t = d ? 127 - i : i;
;         sc_li = GL[(size_t)(d * 8 + h) * 2048 + sc_t]; float inc = GL[(size_t)(d * 8 + 4 + h) * 2048 + sc_t];
; #pragma unroll
;         for (int off = 1; off < 64; off <<= 1) { const float n = __shfl_up(inc, off); inc += (lane >= off) ? n : 0.f; }
;         sc_b = inc; if (lane == 63) wtot[wid] = inc; }
;     ...
;     if (do_store) {
; #pragma unroll 2
;         for (int i = 0; i < 8; ++i) { const int id = tid + 512 * i; const int w = id >> 9, m = (id >> 7) & 3, bj = (id >> 6) & 1, ln = id & 63;
;             *(u32x4*)(Qg + (size_t)((w * 16 + m * 2 + bj) * 64 + ln) * 8) = *(const LAS u32x4*)(Pd + ((w >> 2) * 64 + m * 16 + (ln & 15)) * 264 + bj * 128 + (w & 3) * 32 + (ln >> 4) * 8); } }
.LBB0_568:
	v_add_u32_e32 v3, s0, v196
	v_ashrrev_i32_e32 v5, 5, v3
	v_ashrrev_i32_e32 v4, 9, v3
	v_add_u32_e32 v3, 0x200, v3
	v_and_or_b32 v5, v5, s1, v1
	v_lshlrev_b32_e32 v6, 6, v4
	v_lshlrev_b32_e32 v7, 10, v4
	v_ashrrev_i32_e32 v8, 9, v3
	v_ashrrev_i32_e32 v3, 5, v3
	v_mad_u64_u32 v[4:5], s[6:7], v5, s4, v[0:1]
	v_and_b32_e32 v5, 0xc0, v6
	v_and_or_b32 v3, v3, s1, v1
	v_lshlrev_b32_e32 v6, 6, v8
	v_or3_b32 v12, v7, v2, v197
	v_lshlrev_b32_e32 v7, 10, v8
	v_add3_u32 v8, v4, v5, v200
	v_mad_u64_u32 v[4:5], s[6:7], v3, s4, v[0:1]
	v_and_b32_e32 v3, 0xc0, v6
	v_or3_b32 v14, v7, v2, v197
	v_add3_u32 v3, v4, v3, v200
	ds_read_b128 v[4:7], v8
	ds_read_b128 v[8:11], v3
	s_addk_i32 s0, 0x400
	v_ashrrev_i32_e32 v13, 31, v12
	s_cmpk_lg_i32 s0, 0x1000
	v_lshl_add_u64 v[12:13], v[12:13], 4, s[44:45]
	v_ashrrev_i32_e32 v15, 31, v14
	v_lshl_add_u64 v[14:15], v[14:15], 4, s[44:45]
	s_waitcnt lgkmcnt(1)
	global_store_dwordx4 v[12:13], v[4:7], off
	s_waitcnt lgkmcnt(0)
	global_store_dwordx4 v[14:15], v[8:11], off
	s_cbranch_scc1 .LBB0_568
	v_mov_b32_e32 v196, v224
	s_or_b32 s24, s52, 1
	s_movk_i32 s0, 0x100
	s_barrier
	s_lshl_b32 s10, s24, 7
	v_ashrrev_i32_e32 v68, 6, v196
	v_and_b32_e32 v197, 63, v196
	v_cmp_gt_i32_e64 s[0:1], s0, v196
	v_mov_b32_e32 v63, 0
	v_mov_b32_e32 v69, 0
	v_add_u32_e32 v5, -1, v204
	v_add_u32_e32 v4, -2, v204
	v_add_u32_e32 v3, -4, v204
	v_add_u32_e32 v2, -8, v204
	v_add_u32_e32 v1, -16, v204
	v_subrev_u32_e32 v0, 32, v204
	v_mov_b32_e32 v6, 0
	s_and_saveexec_b64 s[4:5], s[0:1]
	s_cbranch_execz .LBB0_573
	s_ashr_i32 s41, s40, 31
	s_lshl_b64 s[6:7], s[40:41], 17
	s_add_u32 s6, s70, s6
	s_addc_u32 s7, s71, s7
	s_lshl_b32 s11, s10, 2
	s_add_u32 s6, s6, s11
	s_movk_i32 s11, 0x7f
	s_movk_i32 s25, 0x80
	v_and_b32_e32 v6, 0x7f, v196
	v_bitop3_b32 v7, v196, s11, v196 bitop3:0xc
	v_cmp_gt_u32_e32 vcc, s25, v196
	s_addc_u32 s7, s7, 0
	s_add_u32 s6, s6, 0xfc00000
	v_cndmask_b32_e32 v63, v7, v6, vcc
	v_ashrrev_i32_e32 v6, 4, v196
	v_and_or_b32 v6, v6, -8, s34
	v_or_b32_e32 v10, 4, v6
	v_ashrrev_i32_e32 v11, 31, v10
	s_addc_u32 s7, s7, 0
	v_lshlrev_b64 v[10:11], 13, v[10:11]
	v_lshlrev_b32_e32 v8, 2, v63
	v_mov_b32_e32 v9, 0
	v_lshl_add_u64 v[10:11], s[6:7], 0, v[10:11]
	v_lshl_add_u64 v[10:11], v[10:11], 0, v[8:9]
	global_load_dword v10, v[10:11], off
	v_ashrrev_i32_e32 v7, 31, v6
	v_lshlrev_b64 v[6:7], 13, v[6:7]
	v_lshl_add_u64 v[6:7], s[6:7], 0, v[6:7]
	v_lshl_add_u64 v[6:7], v[6:7], 0, v[8:9]
	global_load_dword v6, v[6:7], off
	s_waitcnt vmcnt(1)
	s_nop 1
	v_add_f32_dpp v10, v10, v10 row_shr:1 row_mask:0xf bank_mask:0xf
	s_nop 1
	v_add_f32_dpp v10, v10, v10 row_shr:2 row_mask:0xf bank_mask:0xf
	s_nop 1
	v_add_f32_dpp v10, v10, v10 row_shr:4 row_mask:0xf bank_mask:0xf
	s_nop 1
	v_add_f32_dpp v10, v10, v10 row_shr:8 row_mask:0xf bank_mask:0xf
	s_nop 1
	v_add_f32_dpp v10, v10, v10 row_bcast:15 row_mask:0xa bank_mask:0xf
	s_nop 1
	v_add_f32_dpp v10, v10, v10 row_bcast:31 row_mask:0xc bank_mask:0xf
	v_mov_b32_e32 v69, v10
	v_cmp_eq_u32_e32 vcc, 63, v197
	s_and_saveexec_b64 s[6:7], vcc
	v_lshl_add_u32 v7, v68, 2, 0
	v_add_u32_e32 v7, 0x21800, v7
	ds_write_b32 v7, v69
	s_or_b64 exec, exec, s[6:7]

; __device__ void passB_unit(const Params& p, LAS unsigned char* lds, int u, bool do_store = true) {
;     ...
;     float sc_a = 0.f, sc_pm = 0.f;
;     if (tid < 256) { if (wid & 1) sc_b += wtot[wid - 1];
;         sc_a = sc_li - sc_b; float pm = sc_a;
; #pragma unroll
;         for (int off = 1; off < 64; off <<= 1) { const float n = __shfl_up(pm, off); pm = (lane >= off) ? fmaxf(pm, n) : pm; }
;         sc_pm = pm; if (lane == 63) wmax[wid] = pm; }
.LBB0_576:
	s_or_b64 exec, exec, s[4:5]
	v_sub_f32_e32 v61, v6, v69
	v_cmp_eq_u32_e64 s[4:5], 63, v197
	v_mov_b32_e32 v70, v61
	s_nop 1
	v_max_f32_dpp v70, v70, v70 row_shr:1 row_mask:0xf bank_mask:0xf
	s_nop 1
	v_max_f32_dpp v70, v70, v70 row_shr:2 row_mask:0xf bank_mask:0xf
	s_nop 1
	v_max_f32_dpp v70, v70, v70 row_shr:4 row_mask:0xf bank_mask:0xf
	s_nop 1
	v_max_f32_dpp v70, v70, v70 row_shr:8 row_mask:0xf bank_mask:0xf
	s_nop 1
	v_max_f32_dpp v70, v70, v70 row_bcast:15 row_mask:0xa bank_mask:0xf
	s_nop 1
	v_max_f32_dpp v70, v70, v70 row_bcast:31 row_mask:0xc bank_mask:0xf
	s_and_saveexec_b64 s[10:11], s[4:5]
	v_lshl_add_u32 v2, v68, 2, 0
	v_add_u32_e32 v2, 0x21820, v2
	ds_write_b32 v2, v70
	s_or_b64 exec, exec, s[10:11]
